# P3 prompt-tile-first on workgroups 0-31 plus early decode units on workgroups 224-255
# speedup vs baseline: 1.0043x; 1.0043x over previous
; __device__ __forceinline__ int fresh_lane() { int l; asm volatile("v_mbcnt_lo_u32_b32 %0, -1, 0\n\tv_mbcnt_hi_u32_b32 %0, -1, %0" : "=v"(l)); return l; }
; #define SEAM(k) do { if (IN(k) && IN((k) + 1)) xcd_barrier(bar, C.wave); } while (0)
; #define PH5 { phase_attention(P, C, (P.pad >> 8) & 3, P.li); }
; #define RUN(k, BODY) do { if (IN(k)) { unsigned char* ws = P.ws; LAUNDER_GPTR(ws); BODY } } while (0)
; __device__ __forceinline__ void phase_attention(const Params& P, const Ctx& C, int parts, int qset) {
;     ...
;     for (int i = 0; i < 8; ++i) { const int x = (x0 + i) & 7;
;         for (;;) {
;             __syncthreads();
;             if (C.wave == 0 && fresh_lane() == 0) *slot = __hip_atomic_fetch_add(qc + 64 * x, 1u, __ATOMIC_RELAXED, __HIP_MEMORY_SCOPE_AGENT);
;             __syncthreads();
;             const unsigned u = *slot;
;             if (u >= 128u) break;
;             const int us = __builtin_amdgcn_readfirstlane((int)u);
; __global__ void __launch_bounds__(NWAVES * 64, 2) fwd_kernel(Params P) {
;     ...
;     RUN(3, PH3); SEAM(3);
;     RUN(4, PH4);
;     RUN(5, PH5); SEAM(5);
.LBB0_1136:
	s_bitcmp1_b32 s101, 1
	s_cbranch_scc1 .Lmy_e7
	s_bitset1_b32 s101, 1
	s_cmpk_lg_i32 s68, 0x100
	s_cbranch_scc1 .Lmy_e7
	s_bitset1_b32 s101, 3
	v_readlane_b32 s99, v254, 10
	s_cmpk_lt_u32 s99, 224
	s_cbranch_scc1 .Lmy_e7
	s_and_b32 s100, s99, 31
	s_mul_i32 s100, s100, 4
	s_add_i32 s100, s100, 1
	s_bitset1_b32 s101, 0
	s_waitcnt vmcnt(0)
	s_barrier
	s_mov_b64 s[2:3], -1
	s_branch .LBB0_1192

; __device__ __forceinline__ void phase_attention(const Params& P, const Ctx& C, int parts, int qset) {
;     ...
;             if (pq >= 0) { if (parts & 1) { if (fixed_ok) attn_prompt_unit<true>(P, C, x, pq); else attn_prompt_unit<false>(P, C, x, pq); } }
;             else { if (parts & 2) attn_decode_unit(P, C, x * 64 + dq); }
.LBB0_1215:
	s_bitcmp1_b32 s101, 0
	s_cbranch_scc1 .Lmy_e8
	s_bitcmp1_b32 s101, 3
	s_cbranch_scc0 .Lmy_e8
	v_readlane_b32 s99, v254, 13
	s_add_i32 s99, s99, s4
	s_cmpk_lt_u32 s99, 448
	s_cbranch_scc1 .Lmy_e8
	s_bitcmp0_b32 s4, 0
	s_cbranch_scc1 .LBB0_1200
